# in-proj tile scheduler: divide-by-8 rasterisation step via shift (general reciprocal path kept behind a compare)
# baseline (speedup 1.0000x reference)
.LBB0_353:
	v_readlane_b32 s0, v255, 22
	s_add_i32 s0, s36, s0
	s_lshl_b32 s0, s0, 8
	s_add_i32 s0, s0, s2
	s_ashr_i32 s1, s0, 31
	s_lshr_b32 s1, s1, 29
	s_add_i32 s1, s0, s1
	s_ashr_i32 s6, s1, 3
	s_and_b32 s1, s1, -8
	s_sub_i32 s0, s0, s1
	s_lshr_b32 s1, s0, 31
	s_or_b32 s1, s22, s1
	s_mul_i32 s0, s0, s1
	s_add_i32 s0, s0, s6
	s_abs_i32 s6, s0
	v_readlane_b32 s7, v255, 29
	s_mul_hi_u32 s7, s6, s7
	s_mul_i32 s8, s7, s22
	s_sub_i32 s6, s6, s8
	s_ashr_i32 s1, s0, 31
	s_add_i32 s8, s7, 1
	s_sub_i32 s9, s6, s22
	s_cmp_ge_u32 s6, s22
	s_cselect_b32 s7, s8, s7
	s_cselect_b32 s6, s9, s6
	s_add_i32 s8, s7, 1
	s_cmp_ge_u32 s6, s22
	s_cselect_b32 s6, s8, s7
	s_xor_b32 s6, s6, s1
	s_sub_i32 s1, s6, s1
	s_lshl_b32 s6, s1, 3
	s_sub_i32 s7, 64, s6
	s_min_i32 s7, s7, 8
	s_cmp_lg_u32 s7, 8
	s_cbranch_scc1 .Lts_div_general
	s_mul_i32 s1, s1, s22
	s_sub_i32 s0, s0, s1
	s_abs_i32 s9, s0
	s_ashr_i32 s1, s0, 31
	s_lshr_b32 s8, s9, 3
	s_xor_b32 s8, s8, s1
	s_sub_i32 s52, s8, s1
	s_lshl_b32 s1, s52, 3
	s_sub_i32 s0, s0, s1
	s_add_i32 s54, s0, s6
	s_mov_b64 s[6:7], -1
	s_branch .LBB0_354
.Lts_div_general:
	s_abs_i32 s8, s7
	v_cvt_f32_u32_e32 v48, s8
	s_sub_i32 s10, 0, s8
	s_mul_i32 s1, s1, s22
	s_sub_i32 s0, s0, s1
	v_rcp_iflag_f32_e32 v48, v48
	s_abs_i32 s9, s0
	s_xor_b32 s1, s0, s7
	s_ashr_i32 s1, s1, 31
	v_mul_f32_e32 v48, 0x4f7ffffe, v48
	v_cvt_u32_f32_e32 v48, v48
	s_nop 0
	v_readfirstlane_b32 s11, v48
	s_mul_i32 s10, s10, s11
	s_mul_hi_u32 s10, s11, s10
	s_add_i32 s11, s11, s10
	s_mul_hi_u32 s10, s9, s11
	s_mul_i32 s11, s10, s8
	s_sub_i32 s9, s9, s11
	s_add_i32 s11, s10, 1
	s_sub_i32 s27, s9, s8
	s_cmp_ge_u32 s9, s8
	s_cselect_b32 s10, s11, s10
	s_cselect_b32 s9, s27, s9
	s_add_i32 s11, s10, 1
	s_cmp_ge_u32 s9, s8
	s_cselect_b32 s8, s11, s10
	s_xor_b32 s8, s8, s1
	s_sub_i32 s52, s8, s1
	s_mul_i32 s1, s52, s7
	s_sub_i32 s0, s0, s1
	s_add_i32 s54, s0, s6
	s_mov_b64 s[6:7], -1
